# v083 plus nt hint on the plain / GLU GEMM epilogue stores
# baseline (speedup 1.0000x reference)
; #define SCHED __builtin_amdgcn_sched_barrier(0)
; template <int EPI>
; __device__ __forceinline__ void gemm_tile(const GemmArgs& g, int brow, int bcol, int parity, bool first, bool nvalid, int nbrow, int nbcol) {
;     ...
;   if constexpr (EPI == EPI_PLAIN) {
;     _Pragma("unroll") for (int ai = 0; ai < 2; ++ai) _Pragma("unroll") for (int bj = 0; bj < 2; ++bj) {
;       SCHED;
;       _Pragma("unroll") for (int m = 0; m < 4; ++m) _Pragma("unroll") for (int j = 0; j < 4; ++j) {
;         const float rs = rstd_s[lrow0 + ai * HALF + m * 16 + fq * 4 + j];
;         _Pragma("unroll") for (int n = 0; n < 2; ++n) W_WRITE(m, n, j, acc[ai][bj][m][n][j] * rs);
;       }
;       bfu* dst = g.outb + (long)(wrow0 + ai * HALF) * g.ldo + g.ocol0 + wcol0 + bj * HALF;
;       W_STORE_BF16(dst, g.ldo);
;     }
.LBB0_76:
	v_mbcnt_lo_u32_b32 v130, -1, 0
	v_mbcnt_hi_u32_b32 v130, -1, v130
	s_add_i32 s24, s24, 1
	s_and_b32 s2, s33, 0x100
	s_add_i32 s2, s2, s18
	v_and_b32_e32 v131, 15, v130
	v_lshrrev_b32_e32 v132, 4, v130
	v_lshl_add_u32 v133, v131, 2, s2
	ds_read_b32 v138, v133
	ds_read_b32 v139, v133 offset:64
	ds_read_b32 v140, v133 offset:128
	ds_read_b32 v141, v133 offset:192
	ds_read_b32 v142, v133 offset:512
	ds_read_b32 v143, v133 offset:576
	ds_read_b32 v144, v133 offset:640
	ds_read_b32 v145, v133 offset:704
	v_lshlrev_b32_e32 v134, 4, v132
	v_lshlrev_b32_e32 v135, 2, v132
	v_and_b32_e32 v134, 16, v134
	v_and_b32_e32 v135, 8, v135
	s_and_b32 s3, s34, 0x7fffff8
	s_lshl_b32 s3, s3, 5
	s_lshr_b32 s12, s33, 1
	s_and_b32 s12, s12, 0x60
	s_add_i32 s3, s3, s12
	v_or_b32_e32 v134, v134, v135
	v_add_lshl_u32 v134, v134, s3, 1
	v_mov_b32_e32 v135, 0
	s_lshr_b32 s12, s33, 2
	s_and_b32 s12, s12, 64
	s_add_i32 s12, s12, s38
	v_add_u32_e32 v136, s12, v131
	v_mad_u64_u32 v[134:135], vcc, v136, s89, v[134:135]
	v_lshl_add_u64 v[134:135], v[134:135], 0, s[16:17]
	s_mov_b64 s[12:13], 0x24000
	s_mov_b64 s[14:15], 0xb4000
	s_waitcnt lgkmcnt(0)
	v_pk_mul_f32 v[122:123], v[122:123], v[138:139] op_sel_hi:[1,0]
	v_pk_mul_f32 v[124:125], v[124:125], v[138:139] op_sel_hi:[1,0]
	v_pk_mul_f32 v[126:127], v[126:127], v[138:139] op_sel_hi:[1,0]
	v_pk_mul_f32 v[128:129], v[128:129], v[138:139] op_sel_hi:[1,0]
	v_pk_mul_f32 v[90:91], v[90:91], v[138:139] op_sel_hi:[1,0]
	v_pk_mul_f32 v[92:93], v[92:93], v[138:139] op_sel_hi:[1,0]
	v_pk_mul_f32 v[94:95], v[94:95], v[138:139] op_sel_hi:[1,0]
	v_pk_mul_f32 v[96:97], v[96:97], v[138:139] op_sel_hi:[1,0]
	v_cvt_pk_bf16_f32 v146, v122, v123
	v_cvt_pk_bf16_f32 v147, v124, v125
	v_cvt_pk_bf16_f32 v148, v126, v127
	v_cvt_pk_bf16_f32 v149, v128, v129
	v_cvt_pk_bf16_f32 v150, v90, v91
	v_cvt_pk_bf16_f32 v151, v92, v93
	v_cvt_pk_bf16_f32 v152, v94, v95
	v_cvt_pk_bf16_f32 v153, v96, v97
	v_permlane16_swap_b32_e32 v146, v148
	v_permlane16_swap_b32_e32 v147, v149
	v_permlane16_swap_b32_e32 v150, v152
	v_permlane16_swap_b32_e32 v151, v153
	global_store_dwordx4 v[134:135], v[146:149], off offset:3072 nt
	global_store_dwordx4 v[134:135], v[150:153], off offset:3328 nt
	v_lshl_add_u64 v[134:135], v[134:135], 0, s[12:13]
	v_pk_mul_f32 v[114:115], v[114:115], v[138:139] op_sel:[0,1] op_sel_hi:[1,1]
	v_pk_mul_f32 v[116:117], v[116:117], v[138:139] op_sel:[0,1] op_sel_hi:[1,1]
	v_pk_mul_f32 v[118:119], v[118:119], v[138:139] op_sel:[0,1] op_sel_hi:[1,1]
	v_pk_mul_f32 v[120:121], v[120:121], v[138:139] op_sel:[0,1] op_sel_hi:[1,1]
	v_pk_mul_f32 v[82:83], v[82:83], v[138:139] op_sel:[0,1] op_sel_hi:[1,1]
	v_pk_mul_f32 v[84:85], v[84:85], v[138:139] op_sel:[0,1] op_sel_hi:[1,1]
	v_pk_mul_f32 v[86:87], v[86:87], v[138:139] op_sel:[0,1] op_sel_hi:[1,1]
	v_pk_mul_f32 v[88:89], v[88:89], v[138:139] op_sel:[0,1] op_sel_hi:[1,1]
	v_cvt_pk_bf16_f32 v154, v114, v115
	v_cvt_pk_bf16_f32 v155, v116, v117
	v_cvt_pk_bf16_f32 v156, v118, v119
	v_cvt_pk_bf16_f32 v157, v120, v121
	v_cvt_pk_bf16_f32 v158, v82, v83
	v_cvt_pk_bf16_f32 v159, v84, v85
	v_cvt_pk_bf16_f32 v160, v86, v87
	v_cvt_pk_bf16_f32 v161, v88, v89
	v_permlane16_swap_b32_e32 v154, v156
	v_permlane16_swap_b32_e32 v155, v157
	v_permlane16_swap_b32_e32 v158, v160
	v_permlane16_swap_b32_e32 v159, v161
	global_store_dwordx4 v[134:135], v[154:157], off offset:3072 nt
	global_store_dwordx4 v[134:135], v[158:161], off offset:3328 nt
	v_lshl_add_u64 v[134:135], v[134:135], 0, s[12:13]
	v_pk_mul_f32 v[106:107], v[106:107], v[140:141] op_sel_hi:[1,0]
	v_pk_mul_f32 v[108:109], v[108:109], v[140:141] op_sel_hi:[1,0]
	v_pk_mul_f32 v[110:111], v[110:111], v[140:141] op_sel_hi:[1,0]
	v_pk_mul_f32 v[112:113], v[112:113], v[140:141] op_sel_hi:[1,0]
	v_pk_mul_f32 v[74:75], v[74:75], v[140:141] op_sel_hi:[1,0]
	v_pk_mul_f32 v[76:77], v[76:77], v[140:141] op_sel_hi:[1,0]
	v_pk_mul_f32 v[78:79], v[78:79], v[140:141] op_sel_hi:[1,0]
	v_pk_mul_f32 v[80:81], v[80:81], v[140:141] op_sel_hi:[1,0]
	v_cvt_pk_bf16_f32 v146, v106, v107
	v_cvt_pk_bf16_f32 v147, v108, v109
	v_cvt_pk_bf16_f32 v148, v110, v111
	v_cvt_pk_bf16_f32 v149, v112, v113
	v_cvt_pk_bf16_f32 v150, v74, v75
	v_cvt_pk_bf16_f32 v151, v76, v77
	v_cvt_pk_bf16_f32 v152, v78, v79
	v_cvt_pk_bf16_f32 v153, v80, v81
	v_permlane16_swap_b32_e32 v146, v148
	v_permlane16_swap_b32_e32 v147, v149
	v_permlane16_swap_b32_e32 v150, v152
	v_permlane16_swap_b32_e32 v151, v153
	global_store_dwordx4 v[134:135], v[146:149], off offset:3072 nt
	global_store_dwordx4 v[134:135], v[150:153], off offset:3328 nt
	v_lshl_add_u64 v[134:135], v[134:135], 0, s[12:13]
	v_pk_mul_f32 v[98:99], v[98:99], v[140:141] op_sel:[0,1] op_sel_hi:[1,1]
	v_pk_mul_f32 v[100:101], v[100:101], v[140:141] op_sel:[0,1] op_sel_hi:[1,1]
	v_pk_mul_f32 v[102:103], v[102:103], v[140:141] op_sel:[0,1] op_sel_hi:[1,1]
	v_pk_mul_f32 v[104:105], v[104:105], v[140:141] op_sel:[0,1] op_sel_hi:[1,1]
	v_pk_mul_f32 v[66:67], v[66:67], v[140:141] op_sel:[0,1] op_sel_hi:[1,1]
	v_pk_mul_f32 v[68:69], v[68:69], v[140:141] op_sel:[0,1] op_sel_hi:[1,1]
	v_pk_mul_f32 v[70:71], v[70:71], v[140:141] op_sel:[0,1] op_sel_hi:[1,1]
	v_pk_mul_f32 v[72:73], v[72:73], v[140:141] op_sel:[0,1] op_sel_hi:[1,1]
; #define SCHED __builtin_amdgcn_sched_barrier(0)
; template <int EPI>
; __device__ __forceinline__ void gemm_tile(const GemmArgs& g, int brow, int bcol, int parity, bool first, bool nvalid, int nbrow, int nbcol) {
;     ...
;   if constexpr (EPI == EPI_PLAIN) {
;     _Pragma("unroll") for (int ai = 0; ai < 2; ++ai) _Pragma("unroll") for (int bj = 0; bj < 2; ++bj) {
;       SCHED;
;       _Pragma("unroll") for (int m = 0; m < 4; ++m) _Pragma("unroll") for (int j = 0; j < 4; ++j) {
;         const float rs = rstd_s[lrow0 + ai * HALF + m * 16 + fq * 4 + j];
;         _Pragma("unroll") for (int n = 0; n < 2; ++n) W_WRITE(m, n, j, acc[ai][bj][m][n][j] * rs);
;       }
;       bfu* dst = g.outb + (long)(wrow0 + ai * HALF) * g.ldo + g.ocol0 + wcol0 + bj * HALF;
;       W_STORE_BF16(dst, g.ldo);
;     }
	v_cvt_pk_bf16_f32 v154, v98, v99
	v_cvt_pk_bf16_f32 v155, v100, v101
	v_cvt_pk_bf16_f32 v156, v102, v103
	v_cvt_pk_bf16_f32 v157, v104, v105
	v_cvt_pk_bf16_f32 v158, v66, v67
	v_cvt_pk_bf16_f32 v159, v68, v69
	v_cvt_pk_bf16_f32 v160, v70, v71
	v_cvt_pk_bf16_f32 v161, v72, v73
	v_permlane16_swap_b32_e32 v154, v156
	v_permlane16_swap_b32_e32 v155, v157
	v_permlane16_swap_b32_e32 v158, v160
	v_permlane16_swap_b32_e32 v159, v161
	global_store_dwordx4 v[134:135], v[154:157], off offset:3072 nt
	global_store_dwordx4 v[134:135], v[158:161], off offset:3328 nt
	v_lshl_add_u64 v[134:135], v[134:135], 0, s[14:15]
	v_pk_mul_f32 v[58:59], v[58:59], v[142:143] op_sel_hi:[1,0]
	v_pk_mul_f32 v[60:61], v[60:61], v[142:143] op_sel_hi:[1,0]
	v_pk_mul_f32 v[62:63], v[62:63], v[142:143] op_sel_hi:[1,0]
	v_pk_mul_f32 v[64:65], v[64:65], v[142:143] op_sel_hi:[1,0]
	v_pk_mul_f32 v[26:27], v[26:27], v[142:143] op_sel_hi:[1,0]
	v_pk_mul_f32 v[28:29], v[28:29], v[142:143] op_sel_hi:[1,0]
	v_pk_mul_f32 v[30:31], v[30:31], v[142:143] op_sel_hi:[1,0]
	v_pk_mul_f32 v[32:33], v[32:33], v[142:143] op_sel_hi:[1,0]
	v_cvt_pk_bf16_f32 v146, v58, v59
	v_cvt_pk_bf16_f32 v147, v60, v61
	v_cvt_pk_bf16_f32 v148, v62, v63
	v_cvt_pk_bf16_f32 v149, v64, v65
	v_cvt_pk_bf16_f32 v150, v26, v27
	v_cvt_pk_bf16_f32 v151, v28, v29
	v_cvt_pk_bf16_f32 v152, v30, v31
	v_cvt_pk_bf16_f32 v153, v32, v33
	v_permlane16_swap_b32_e32 v146, v148
	v_permlane16_swap_b32_e32 v147, v149
	v_permlane16_swap_b32_e32 v150, v152
	v_permlane16_swap_b32_e32 v151, v153
	global_store_dwordx4 v[134:135], v[146:149], off offset:3072 nt
	global_store_dwordx4 v[134:135], v[150:153], off offset:3328 nt
	v_lshl_add_u64 v[134:135], v[134:135], 0, s[12:13]
	v_pk_mul_f32 v[50:51], v[50:51], v[142:143] op_sel:[0,1] op_sel_hi:[1,1]
	v_pk_mul_f32 v[52:53], v[52:53], v[142:143] op_sel:[0,1] op_sel_hi:[1,1]
	v_pk_mul_f32 v[54:55], v[54:55], v[142:143] op_sel:[0,1] op_sel_hi:[1,1]
	v_pk_mul_f32 v[56:57], v[56:57], v[142:143] op_sel:[0,1] op_sel_hi:[1,1]
	v_pk_mul_f32 v[18:19], v[18:19], v[142:143] op_sel:[0,1] op_sel_hi:[1,1]
	v_pk_mul_f32 v[20:21], v[20:21], v[142:143] op_sel:[0,1] op_sel_hi:[1,1]
	v_pk_mul_f32 v[22:23], v[22:23], v[142:143] op_sel:[0,1] op_sel_hi:[1,1]
	v_pk_mul_f32 v[24:25], v[24:25], v[142:143] op_sel:[0,1] op_sel_hi:[1,1]
	v_cvt_pk_bf16_f32 v154, v50, v51
	v_cvt_pk_bf16_f32 v155, v52, v53
	v_cvt_pk_bf16_f32 v156, v54, v55
	v_cvt_pk_bf16_f32 v157, v56, v57
	v_cvt_pk_bf16_f32 v158, v18, v19
	v_cvt_pk_bf16_f32 v159, v20, v21
	v_cvt_pk_bf16_f32 v160, v22, v23
	v_cvt_pk_bf16_f32 v161, v24, v25
	v_permlane16_swap_b32_e32 v154, v156
	v_permlane16_swap_b32_e32 v155, v157
	v_permlane16_swap_b32_e32 v158, v160
	v_permlane16_swap_b32_e32 v159, v161
	global_store_dwordx4 v[134:135], v[154:157], off offset:3072 nt
	global_store_dwordx4 v[134:135], v[158:161], off offset:3328 nt
	v_lshl_add_u64 v[134:135], v[134:135], 0, s[12:13]
	v_pk_mul_f32 v[42:43], v[42:43], v[144:145] op_sel_hi:[1,0]
	v_pk_mul_f32 v[44:45], v[44:45], v[144:145] op_sel_hi:[1,0]
	v_pk_mul_f32 v[46:47], v[46:47], v[144:145] op_sel_hi:[1,0]
	v_pk_mul_f32 v[48:49], v[48:49], v[144:145] op_sel_hi:[1,0]
	v_pk_mul_f32 v[10:11], v[10:11], v[144:145] op_sel_hi:[1,0]
	v_pk_mul_f32 v[12:13], v[12:13], v[144:145] op_sel_hi:[1,0]
	v_pk_mul_f32 v[14:15], v[14:15], v[144:145] op_sel_hi:[1,0]
	v_pk_mul_f32 v[16:17], v[16:17], v[144:145] op_sel_hi:[1,0]
	v_cvt_pk_bf16_f32 v146, v42, v43
	v_cvt_pk_bf16_f32 v147, v44, v45
	v_cvt_pk_bf16_f32 v148, v46, v47
	v_cvt_pk_bf16_f32 v149, v48, v49
	v_cvt_pk_bf16_f32 v150, v10, v11
	v_cvt_pk_bf16_f32 v151, v12, v13
	v_cvt_pk_bf16_f32 v152, v14, v15
	v_cvt_pk_bf16_f32 v153, v16, v17
	v_permlane16_swap_b32_e32 v146, v148
	v_permlane16_swap_b32_e32 v147, v149
	v_permlane16_swap_b32_e32 v150, v152
	v_permlane16_swap_b32_e32 v151, v153
	global_store_dwordx4 v[134:135], v[146:149], off offset:3072 nt
	global_store_dwordx4 v[134:135], v[150:153], off offset:3328 nt
	v_lshl_add_u64 v[134:135], v[134:135], 0, s[12:13]
	v_pk_mul_f32 v[34:35], v[34:35], v[144:145] op_sel:[0,1] op_sel_hi:[1,1]
	v_pk_mul_f32 v[36:37], v[36:37], v[144:145] op_sel:[0,1] op_sel_hi:[1,1]
	v_pk_mul_f32 v[38:39], v[38:39], v[144:145] op_sel:[0,1] op_sel_hi:[1,1]
	v_pk_mul_f32 v[40:41], v[40:41], v[144:145] op_sel:[0,1] op_sel_hi:[1,1]
	v_pk_mul_f32 v[2:3], v[2:3], v[144:145] op_sel:[0,1] op_sel_hi:[1,1]
	v_pk_mul_f32 v[4:5], v[4:5], v[144:145] op_sel:[0,1] op_sel_hi:[1,1]
	v_pk_mul_f32 v[6:7], v[6:7], v[144:145] op_sel:[0,1] op_sel_hi:[1,1]
	v_pk_mul_f32 v[8:9], v[8:9], v[144:145] op_sel:[0,1] op_sel_hi:[1,1]
	v_cvt_pk_bf16_f32 v154, v34, v35
	v_cvt_pk_bf16_f32 v155, v36, v37
	v_cvt_pk_bf16_f32 v156, v38, v39
	v_cvt_pk_bf16_f32 v157, v40, v41
	v_cvt_pk_bf16_f32 v158, v2, v3
	v_cvt_pk_bf16_f32 v159, v4, v5
	v_cvt_pk_bf16_f32 v160, v6, v7
	v_cvt_pk_bf16_f32 v161, v8, v9
	v_permlane16_swap_b32_e32 v154, v156
	v_permlane16_swap_b32_e32 v155, v157
	v_permlane16_swap_b32_e32 v158, v160
	v_permlane16_swap_b32_e32 v159, v161
	global_store_dwordx4 v[134:135], v[154:157], off offset:3072 nt
	global_store_dwordx4 v[134:135], v[158:161], off offset:3328 nt
	s_mov_b64 s[14:15], -1
	s_and_b64 vcc, exec, s[0:1]
	s_cbranch_vccnz .LBB0_95

; __device__ __forceinline__ float siluf_(float x) { return x * frcp(1.0f + fexp(-x)); }
; #define SCHED __builtin_amdgcn_sched_barrier(0)
; template <int EPI>
; __device__ __forceinline__ void gemm_tile(const GemmArgs& g, int brow, int bcol, int parity, bool first, bool nvalid, int nbrow, int nbcol) {
;     ...
;   } else if constexpr (EPI == EPI_GLU) {
;     const int tn = bcol >> 8;
;     _Pragma("unroll") for (int ai = 0; ai < 2; ++ai) {
;       SCHED;
;       _Pragma("unroll") for (int m = 0; m < 4; ++m) _Pragma("unroll") for (int j = 0; j < 4; ++j) {
;         const float rs = rstd_s[lrow0 + ai * HALF + m * 16 + fq * 4 + j];
;         _Pragma("unroll") for (int n = 0; n < 2; ++n) {
;           const float gg = acc[ai][0][m][n][j] * rs, uu = acc[ai][1][m][n][j] * rs;
;           W_WRITE(m, n, j, siluf_(gg) * uu);
;         }
;       }
;       bfu* dst = g.outb + (long)(wrow0 + ai * HALF) * g.ldo + tn * 128 + (wcol0 - bcol);
;       W_STORE_BF16(dst, g.ldo);
;     }
.LBB0_152:
	v_mbcnt_lo_u32_b32 v130, -1, 0
	v_mbcnt_hi_u32_b32 v130, -1, v130
	s_add_i32 s24, s24, 1
	s_and_b32 s2, s33, 0x100
	s_add_i32 s2, s2, s14
	v_and_b32_e32 v131, 15, v130
	v_lshrrev_b32_e32 v132, 4, v130
	v_lshl_add_u32 v133, v131, 2, s2
	ds_read_b32 v138, v133
	ds_read_b32 v139, v133 offset:64
	ds_read_b32 v140, v133 offset:128
	ds_read_b32 v141, v133 offset:192
	ds_read_b32 v142, v133 offset:512
	ds_read_b32 v143, v133 offset:576
	ds_read_b32 v144, v133 offset:640
	ds_read_b32 v145, v133 offset:704
	v_lshlrev_b32_e32 v134, 4, v132
	v_lshlrev_b32_e32 v135, 2, v132
	v_and_b32_e32 v134, 16, v134
	v_and_b32_e32 v135, 8, v135
	s_lshl_b32 s3, s34, 4
	s_and_b32 s3, s3, 0xffffff80
	s_lshr_b32 s12, s33, 1
	s_and_b32 s12, s12, 0x60
	s_add_i32 s3, s3, s12
	v_or_b32_e32 v134, v134, v135
	v_add_lshl_u32 v134, v134, s3, 1
	v_mov_b32_e32 v135, 0
	s_lshr_b32 s12, s33, 2
	s_and_b32 s12, s12, 64
	s_add_i32 s12, s12, s38
	v_add_u32_e32 v136, s12, v131
	s_movk_i32 s3, 0x1600
	v_mad_u64_u32 v[134:135], vcc, v136, s3, v[134:135]
	v_lshl_add_u64 v[134:135], v[134:135], 0, s[16:17]
	s_mov_b64 s[12:13], 0x16000
	s_mov_b64 s[14:15], 0x6e000
	v_mov_b32_e32 v146, 0xbfb8aa3b
	v_mov_b32_e32 v147, 1.0
	s_waitcnt lgkmcnt(0)
	v_pk_mul_f32 v[122:123], v[122:123], v[138:139] op_sel_hi:[1,0]
	v_pk_mul_f32 v[124:125], v[124:125], v[138:139] op_sel_hi:[1,0]
	v_pk_mul_f32 v[114:115], v[114:115], v[138:139] op_sel_hi:[1,0]
	v_pk_mul_f32 v[116:117], v[116:117], v[138:139] op_sel_hi:[1,0]
	v_pk_mul_f32 v[126:127], v[126:127], v[138:139] op_sel_hi:[1,0]
	v_pk_mul_f32 v[128:129], v[128:129], v[138:139] op_sel_hi:[1,0]
	v_pk_mul_f32 v[118:119], v[118:119], v[138:139] op_sel_hi:[1,0]
	v_pk_mul_f32 v[120:121], v[120:121], v[138:139] op_sel_hi:[1,0]
	v_pk_mul_f32 v[148:149], v[122:123], v[146:147] op_sel_hi:[1,0]
	v_pk_mul_f32 v[150:151], v[124:125], v[146:147] op_sel_hi:[1,0]
	v_pk_mul_f32 v[152:153], v[114:115], v[146:147] op_sel_hi:[1,0]
	v_pk_mul_f32 v[154:155], v[116:117], v[146:147] op_sel_hi:[1,0]
	v_exp_f32_e32 v148, v148
	v_exp_f32_e32 v149, v149
	v_exp_f32_e32 v150, v150
	v_exp_f32_e32 v151, v151
	v_exp_f32_e32 v152, v152
	v_exp_f32_e32 v153, v153
	v_exp_f32_e32 v154, v154
	v_exp_f32_e32 v155, v155
	v_pk_add_f32 v[148:149], v[148:149], v[146:147] op_sel:[0,1] op_sel_hi:[1,1]
	v_pk_add_f32 v[150:151], v[150:151], v[146:147] op_sel:[0,1] op_sel_hi:[1,1]
	v_pk_add_f32 v[152:153], v[152:153], v[146:147] op_sel:[0,1] op_sel_hi:[1,1]
	v_pk_add_f32 v[154:155], v[154:155], v[146:147] op_sel:[0,1] op_sel_hi:[1,1]
	v_rcp_f32_e32 v148, v148
	v_rcp_f32_e32 v149, v149
	v_rcp_f32_e32 v150, v150
	v_rcp_f32_e32 v151, v151
	v_rcp_f32_e32 v152, v152
	v_rcp_f32_e32 v153, v153
	v_rcp_f32_e32 v154, v154
	v_rcp_f32_e32 v155, v155
	v_pk_mul_f32 v[122:123], v[122:123], v[148:149]
	v_pk_mul_f32 v[124:125], v[124:125], v[150:151]
	v_pk_mul_f32 v[114:115], v[114:115], v[152:153]
	v_pk_mul_f32 v[116:117], v[116:117], v[154:155]
	v_pk_mul_f32 v[122:123], v[126:127], v[122:123]
	v_pk_mul_f32 v[124:125], v[128:129], v[124:125]
	v_pk_mul_f32 v[114:115], v[118:119], v[114:115]
	v_pk_mul_f32 v[116:117], v[120:121], v[116:117]
	v_cvt_pk_bf16_f32 v156, v122, v123
	v_cvt_pk_bf16_f32 v157, v124, v125
	v_cvt_pk_bf16_f32 v158, v114, v115
	v_cvt_pk_bf16_f32 v159, v116, v117
	v_pk_mul_f32 v[106:107], v[106:107], v[138:139] op_sel:[0,1] op_sel_hi:[1,1]
	v_pk_mul_f32 v[108:109], v[108:109], v[138:139] op_sel:[0,1] op_sel_hi:[1,1]
	v_pk_mul_f32 v[98:99], v[98:99], v[138:139] op_sel:[0,1] op_sel_hi:[1,1]
	v_pk_mul_f32 v[100:101], v[100:101], v[138:139] op_sel:[0,1] op_sel_hi:[1,1]
	v_pk_mul_f32 v[110:111], v[110:111], v[138:139] op_sel:[0,1] op_sel_hi:[1,1]
	v_pk_mul_f32 v[112:113], v[112:113], v[138:139] op_sel:[0,1] op_sel_hi:[1,1]
	v_pk_mul_f32 v[102:103], v[102:103], v[138:139] op_sel:[0,1] op_sel_hi:[1,1]
	v_pk_mul_f32 v[104:105], v[104:105], v[138:139] op_sel:[0,1] op_sel_hi:[1,1]
	v_permlane16_swap_b32_e32 v156, v158
	v_permlane16_swap_b32_e32 v157, v159
	global_store_dwordx4 v[134:135], v[156:159], off nt
	v_lshl_add_u64 v[134:135], v[134:135], 0, s[12:13]
	v_pk_mul_f32 v[148:149], v[106:107], v[146:147] op_sel_hi:[1,0]
	v_pk_mul_f32 v[150:151], v[108:109], v[146:147] op_sel_hi:[1,0]
	v_pk_mul_f32 v[152:153], v[98:99], v[146:147] op_sel_hi:[1,0]
	v_pk_mul_f32 v[154:155], v[100:101], v[146:147] op_sel_hi:[1,0]
	v_exp_f32_e32 v148, v148
	v_exp_f32_e32 v149, v149
	v_exp_f32_e32 v150, v150
	v_exp_f32_e32 v151, v151
	v_exp_f32_e32 v152, v152
	v_exp_f32_e32 v153, v153
	v_exp_f32_e32 v154, v154
	v_exp_f32_e32 v155, v155
	v_pk_add_f32 v[148:149], v[148:149], v[146:147] op_sel:[0,1] op_sel_hi:[1,1]
	v_pk_add_f32 v[150:151], v[150:151], v[146:147] op_sel:[0,1] op_sel_hi:[1,1]
	v_pk_add_f32 v[152:153], v[152:153], v[146:147] op_sel:[0,1] op_sel_hi:[1,1]
	v_pk_add_f32 v[154:155], v[154:155], v[146:147] op_sel:[0,1] op_sel_hi:[1,1]
	v_rcp_f32_e32 v148, v148
	v_rcp_f32_e32 v149, v149
	v_rcp_f32_e32 v150, v150
	v_rcp_f32_e32 v151, v151
	v_rcp_f32_e32 v152, v152
	v_rcp_f32_e32 v153, v153
	v_rcp_f32_e32 v154, v154
	v_rcp_f32_e32 v155, v155
	v_pk_mul_f32 v[106:107], v[106:107], v[148:149]
	v_pk_mul_f32 v[108:109], v[108:109], v[150:151]
	v_pk_mul_f32 v[98:99], v[98:99], v[152:153]
	v_pk_mul_f32 v[100:101], v[100:101], v[154:155]
	v_pk_mul_f32 v[106:107], v[110:111], v[106:107]
	v_pk_mul_f32 v[108:109], v[112:113], v[108:109]
	v_pk_mul_f32 v[98:99], v[102:103], v[98:99]
	v_pk_mul_f32 v[100:101], v[104:105], v[100:101]
	v_cvt_pk_bf16_f32 v160, v106, v107
	v_cvt_pk_bf16_f32 v161, v108, v109
	v_cvt_pk_bf16_f32 v162, v98, v99
	v_cvt_pk_bf16_f32 v163, v100, v101
	v_pk_mul_f32 v[90:91], v[90:91], v[140:141] op_sel_hi:[1,0]
; __device__ __forceinline__ float siluf_(float x) { return x * frcp(1.0f + fexp(-x)); }
; #define SCHED __builtin_amdgcn_sched_barrier(0)
; template <int EPI>
; __device__ __forceinline__ void gemm_tile(const GemmArgs& g, int brow, int bcol, int parity, bool first, bool nvalid, int nbrow, int nbcol) {
;     ...
;   } else if constexpr (EPI == EPI_GLU) {
;     const int tn = bcol >> 8;
;     _Pragma("unroll") for (int ai = 0; ai < 2; ++ai) {
;       SCHED;
;       _Pragma("unroll") for (int m = 0; m < 4; ++m) _Pragma("unroll") for (int j = 0; j < 4; ++j) {
;         const float rs = rstd_s[lrow0 + ai * HALF + m * 16 + fq * 4 + j];
;         _Pragma("unroll") for (int n = 0; n < 2; ++n) {
;           const float gg = acc[ai][0][m][n][j] * rs, uu = acc[ai][1][m][n][j] * rs;
;           W_WRITE(m, n, j, siluf_(gg) * uu);
;         }
;       }
;       bfu* dst = g.outb + (long)(wrow0 + ai * HALF) * g.ldo + tn * 128 + (wcol0 - bcol);
;       W_STORE_BF16(dst, g.ldo);
;     }
	v_pk_mul_f32 v[92:93], v[92:93], v[140:141] op_sel_hi:[1,0]
	v_pk_mul_f32 v[82:83], v[82:83], v[140:141] op_sel_hi:[1,0]
	v_pk_mul_f32 v[84:85], v[84:85], v[140:141] op_sel_hi:[1,0]
	v_pk_mul_f32 v[94:95], v[94:95], v[140:141] op_sel_hi:[1,0]
	v_pk_mul_f32 v[96:97], v[96:97], v[140:141] op_sel_hi:[1,0]
	v_pk_mul_f32 v[86:87], v[86:87], v[140:141] op_sel_hi:[1,0]
	v_pk_mul_f32 v[88:89], v[88:89], v[140:141] op_sel_hi:[1,0]
	v_permlane16_swap_b32_e32 v160, v162
	v_permlane16_swap_b32_e32 v161, v163
	global_store_dwordx4 v[134:135], v[160:163], off nt
	v_lshl_add_u64 v[134:135], v[134:135], 0, s[12:13]
	v_pk_mul_f32 v[148:149], v[90:91], v[146:147] op_sel_hi:[1,0]
	v_pk_mul_f32 v[150:151], v[92:93], v[146:147] op_sel_hi:[1,0]
	v_pk_mul_f32 v[152:153], v[82:83], v[146:147] op_sel_hi:[1,0]
	v_pk_mul_f32 v[154:155], v[84:85], v[146:147] op_sel_hi:[1,0]
	v_exp_f32_e32 v148, v148
	v_exp_f32_e32 v149, v149
	v_exp_f32_e32 v150, v150
	v_exp_f32_e32 v151, v151
	v_exp_f32_e32 v152, v152
	v_exp_f32_e32 v153, v153
	v_exp_f32_e32 v154, v154
	v_exp_f32_e32 v155, v155
	v_pk_add_f32 v[148:149], v[148:149], v[146:147] op_sel:[0,1] op_sel_hi:[1,1]
	v_pk_add_f32 v[150:151], v[150:151], v[146:147] op_sel:[0,1] op_sel_hi:[1,1]
	v_pk_add_f32 v[152:153], v[152:153], v[146:147] op_sel:[0,1] op_sel_hi:[1,1]
	v_pk_add_f32 v[154:155], v[154:155], v[146:147] op_sel:[0,1] op_sel_hi:[1,1]
	v_rcp_f32_e32 v148, v148
	v_rcp_f32_e32 v149, v149
	v_rcp_f32_e32 v150, v150
	v_rcp_f32_e32 v151, v151
	v_rcp_f32_e32 v152, v152
	v_rcp_f32_e32 v153, v153
	v_rcp_f32_e32 v154, v154
	v_rcp_f32_e32 v155, v155
	v_pk_mul_f32 v[90:91], v[90:91], v[148:149]
	v_pk_mul_f32 v[92:93], v[92:93], v[150:151]
	v_pk_mul_f32 v[82:83], v[82:83], v[152:153]
	v_pk_mul_f32 v[84:85], v[84:85], v[154:155]
	v_pk_mul_f32 v[90:91], v[94:95], v[90:91]
	v_pk_mul_f32 v[92:93], v[96:97], v[92:93]
	v_pk_mul_f32 v[82:83], v[86:87], v[82:83]
	v_pk_mul_f32 v[84:85], v[88:89], v[84:85]
	v_cvt_pk_bf16_f32 v156, v90, v91
	v_cvt_pk_bf16_f32 v157, v92, v93
	v_cvt_pk_bf16_f32 v158, v82, v83
	v_cvt_pk_bf16_f32 v159, v84, v85
	v_pk_mul_f32 v[70:71], v[70:71], v[140:141] op_sel:[0,1] op_sel_hi:[1,1]
	v_pk_mul_f32 v[72:73], v[72:73], v[140:141] op_sel:[0,1] op_sel_hi:[1,1]
	v_pk_mul_f32 v[66:67], v[66:67], v[140:141] op_sel:[0,1] op_sel_hi:[1,1]
	v_pk_mul_f32 v[68:69], v[68:69], v[140:141] op_sel:[0,1] op_sel_hi:[1,1]
	v_pk_mul_f32 v[78:79], v[78:79], v[140:141] op_sel:[0,1] op_sel_hi:[1,1]
	v_pk_mul_f32 v[80:81], v[80:81], v[140:141] op_sel:[0,1] op_sel_hi:[1,1]
	v_pk_mul_f32 v[74:75], v[74:75], v[140:141] op_sel:[0,1] op_sel_hi:[1,1]
	v_pk_mul_f32 v[76:77], v[76:77], v[140:141] op_sel:[0,1] op_sel_hi:[1,1]
	v_permlane16_swap_b32_e32 v156, v158
	v_permlane16_swap_b32_e32 v157, v159
	global_store_dwordx4 v[134:135], v[156:159], off nt
	v_lshl_add_u64 v[134:135], v[134:135], 0, s[12:13]
	v_pk_mul_f32 v[148:149], v[70:71], v[146:147] op_sel_hi:[1,0]
	v_pk_mul_f32 v[150:151], v[72:73], v[146:147] op_sel_hi:[1,0]
	v_pk_mul_f32 v[152:153], v[66:67], v[146:147] op_sel_hi:[1,0]
	v_pk_mul_f32 v[154:155], v[68:69], v[146:147] op_sel_hi:[1,0]
	v_exp_f32_e32 v148, v148
	v_exp_f32_e32 v149, v149
	v_exp_f32_e32 v150, v150
	v_exp_f32_e32 v151, v151
	v_exp_f32_e32 v152, v152
	v_exp_f32_e32 v153, v153
	v_exp_f32_e32 v154, v154
	v_exp_f32_e32 v155, v155
	v_pk_add_f32 v[148:149], v[148:149], v[146:147] op_sel:[0,1] op_sel_hi:[1,1]
	v_pk_add_f32 v[150:151], v[150:151], v[146:147] op_sel:[0,1] op_sel_hi:[1,1]
	v_pk_add_f32 v[152:153], v[152:153], v[146:147] op_sel:[0,1] op_sel_hi:[1,1]
	v_pk_add_f32 v[154:155], v[154:155], v[146:147] op_sel:[0,1] op_sel_hi:[1,1]
	v_rcp_f32_e32 v148, v148
	v_rcp_f32_e32 v149, v149
	v_rcp_f32_e32 v150, v150
	v_rcp_f32_e32 v151, v151
	v_rcp_f32_e32 v152, v152
	v_rcp_f32_e32 v153, v153
	v_rcp_f32_e32 v154, v154
	v_rcp_f32_e32 v155, v155
	v_pk_mul_f32 v[70:71], v[70:71], v[148:149]
	v_pk_mul_f32 v[72:73], v[72:73], v[150:151]
	v_pk_mul_f32 v[66:67], v[66:67], v[152:153]
	v_pk_mul_f32 v[68:69], v[68:69], v[154:155]
	v_pk_mul_f32 v[70:71], v[78:79], v[70:71]
	v_pk_mul_f32 v[72:73], v[80:81], v[72:73]
	v_pk_mul_f32 v[66:67], v[74:75], v[66:67]
	v_pk_mul_f32 v[68:69], v[76:77], v[68:69]
	v_cvt_pk_bf16_f32 v160, v70, v71
	v_cvt_pk_bf16_f32 v161, v72, v73
	v_cvt_pk_bf16_f32 v162, v66, v67
	v_cvt_pk_bf16_f32 v163, v68, v69
	v_pk_mul_f32 v[58:59], v[58:59], v[142:143] op_sel_hi:[1,0]
	v_pk_mul_f32 v[60:61], v[60:61], v[142:143] op_sel_hi:[1,0]
	v_pk_mul_f32 v[50:51], v[50:51], v[142:143] op_sel_hi:[1,0]
	v_pk_mul_f32 v[52:53], v[52:53], v[142:143] op_sel_hi:[1,0]
	v_pk_mul_f32 v[62:63], v[62:63], v[142:143] op_sel_hi:[1,0]
	v_pk_mul_f32 v[64:65], v[64:65], v[142:143] op_sel_hi:[1,0]
	v_pk_mul_f32 v[54:55], v[54:55], v[142:143] op_sel_hi:[1,0]
	v_pk_mul_f32 v[56:57], v[56:57], v[142:143] op_sel_hi:[1,0]
	v_permlane16_swap_b32_e32 v160, v162
	v_permlane16_swap_b32_e32 v161, v163
	global_store_dwordx4 v[134:135], v[160:163], off nt
	v_lshl_add_u64 v[134:135], v[134:135], 0, s[14:15]
	v_pk_mul_f32 v[148:149], v[58:59], v[146:147] op_sel_hi:[1,0]
	v_pk_mul_f32 v[150:151], v[60:61], v[146:147] op_sel_hi:[1,0]
	v_pk_mul_f32 v[152:153], v[50:51], v[146:147] op_sel_hi:[1,0]
	v_pk_mul_f32 v[154:155], v[52:53], v[146:147] op_sel_hi:[1,0]
	v_exp_f32_e32 v148, v148
	v_exp_f32_e32 v149, v149
	v_exp_f32_e32 v150, v150
	v_exp_f32_e32 v151, v151
	v_exp_f32_e32 v152, v152
	v_exp_f32_e32 v153, v153
	v_exp_f32_e32 v154, v154
	v_exp_f32_e32 v155, v155
	v_pk_add_f32 v[148:149], v[148:149], v[146:147] op_sel:[0,1] op_sel_hi:[1,1]
	v_pk_add_f32 v[150:151], v[150:151], v[146:147] op_sel:[0,1] op_sel_hi:[1,1]
; __device__ __forceinline__ float siluf_(float x) { return x * frcp(1.0f + fexp(-x)); }
; #define SCHED __builtin_amdgcn_sched_barrier(0)
; template <int EPI>
; __device__ __forceinline__ void gemm_tile(const GemmArgs& g, int brow, int bcol, int parity, bool first, bool nvalid, int nbrow, int nbcol) {
;     ...
;   } else if constexpr (EPI == EPI_GLU) {
;     const int tn = bcol >> 8;
;     _Pragma("unroll") for (int ai = 0; ai < 2; ++ai) {
;       SCHED;
;       _Pragma("unroll") for (int m = 0; m < 4; ++m) _Pragma("unroll") for (int j = 0; j < 4; ++j) {
;         const float rs = rstd_s[lrow0 + ai * HALF + m * 16 + fq * 4 + j];
;         _Pragma("unroll") for (int n = 0; n < 2; ++n) {
;           const float gg = acc[ai][0][m][n][j] * rs, uu = acc[ai][1][m][n][j] * rs;
;           W_WRITE(m, n, j, siluf_(gg) * uu);
;         }
;       }
;       bfu* dst = g.outb + (long)(wrow0 + ai * HALF) * g.ldo + tn * 128 + (wcol0 - bcol);
;       W_STORE_BF16(dst, g.ldo);
;     }
	v_pk_add_f32 v[152:153], v[152:153], v[146:147] op_sel:[0,1] op_sel_hi:[1,1]
	v_pk_add_f32 v[154:155], v[154:155], v[146:147] op_sel:[0,1] op_sel_hi:[1,1]
	v_rcp_f32_e32 v148, v148
	v_rcp_f32_e32 v149, v149
	v_rcp_f32_e32 v150, v150
	v_rcp_f32_e32 v151, v151
	v_rcp_f32_e32 v152, v152
	v_rcp_f32_e32 v153, v153
	v_rcp_f32_e32 v154, v154
	v_rcp_f32_e32 v155, v155
	v_pk_mul_f32 v[58:59], v[58:59], v[148:149]
	v_pk_mul_f32 v[60:61], v[60:61], v[150:151]
	v_pk_mul_f32 v[50:51], v[50:51], v[152:153]
	v_pk_mul_f32 v[52:53], v[52:53], v[154:155]
	v_pk_mul_f32 v[58:59], v[62:63], v[58:59]
	v_pk_mul_f32 v[60:61], v[64:65], v[60:61]
	v_pk_mul_f32 v[50:51], v[54:55], v[50:51]
	v_pk_mul_f32 v[52:53], v[56:57], v[52:53]
	v_cvt_pk_bf16_f32 v156, v58, v59
	v_cvt_pk_bf16_f32 v157, v60, v61
	v_cvt_pk_bf16_f32 v158, v50, v51
	v_cvt_pk_bf16_f32 v159, v52, v53
	v_pk_mul_f32 v[42:43], v[42:43], v[142:143] op_sel:[0,1] op_sel_hi:[1,1]
	v_pk_mul_f32 v[44:45], v[44:45], v[142:143] op_sel:[0,1] op_sel_hi:[1,1]
	v_pk_mul_f32 v[34:35], v[34:35], v[142:143] op_sel:[0,1] op_sel_hi:[1,1]
	v_pk_mul_f32 v[36:37], v[36:37], v[142:143] op_sel:[0,1] op_sel_hi:[1,1]
	v_pk_mul_f32 v[46:47], v[46:47], v[142:143] op_sel:[0,1] op_sel_hi:[1,1]
	v_pk_mul_f32 v[48:49], v[48:49], v[142:143] op_sel:[0,1] op_sel_hi:[1,1]
	v_pk_mul_f32 v[38:39], v[38:39], v[142:143] op_sel:[0,1] op_sel_hi:[1,1]
	v_pk_mul_f32 v[40:41], v[40:41], v[142:143] op_sel:[0,1] op_sel_hi:[1,1]
	v_permlane16_swap_b32_e32 v156, v158
	v_permlane16_swap_b32_e32 v157, v159
	global_store_dwordx4 v[134:135], v[156:159], off nt
	v_lshl_add_u64 v[134:135], v[134:135], 0, s[12:13]
	v_pk_mul_f32 v[148:149], v[42:43], v[146:147] op_sel_hi:[1,0]
	v_pk_mul_f32 v[150:151], v[44:45], v[146:147] op_sel_hi:[1,0]
	v_pk_mul_f32 v[152:153], v[34:35], v[146:147] op_sel_hi:[1,0]
	v_pk_mul_f32 v[154:155], v[36:37], v[146:147] op_sel_hi:[1,0]
	v_exp_f32_e32 v148, v148
	v_exp_f32_e32 v149, v149
	v_exp_f32_e32 v150, v150
	v_exp_f32_e32 v151, v151
	v_exp_f32_e32 v152, v152
	v_exp_f32_e32 v153, v153
	v_exp_f32_e32 v154, v154
	v_exp_f32_e32 v155, v155
	v_pk_add_f32 v[148:149], v[148:149], v[146:147] op_sel:[0,1] op_sel_hi:[1,1]
	v_pk_add_f32 v[150:151], v[150:151], v[146:147] op_sel:[0,1] op_sel_hi:[1,1]
	v_pk_add_f32 v[152:153], v[152:153], v[146:147] op_sel:[0,1] op_sel_hi:[1,1]
	v_pk_add_f32 v[154:155], v[154:155], v[146:147] op_sel:[0,1] op_sel_hi:[1,1]
	v_rcp_f32_e32 v148, v148
	v_rcp_f32_e32 v149, v149
	v_rcp_f32_e32 v150, v150
	v_rcp_f32_e32 v151, v151
	v_rcp_f32_e32 v152, v152
	v_rcp_f32_e32 v153, v153
	v_rcp_f32_e32 v154, v154
	v_rcp_f32_e32 v155, v155
	v_pk_mul_f32 v[42:43], v[42:43], v[148:149]
	v_pk_mul_f32 v[44:45], v[44:45], v[150:151]
	v_pk_mul_f32 v[34:35], v[34:35], v[152:153]
	v_pk_mul_f32 v[36:37], v[36:37], v[154:155]
	v_pk_mul_f32 v[42:43], v[46:47], v[42:43]
	v_pk_mul_f32 v[44:45], v[48:49], v[44:45]
	v_pk_mul_f32 v[34:35], v[38:39], v[34:35]
	v_pk_mul_f32 v[36:37], v[40:41], v[36:37]
	v_cvt_pk_bf16_f32 v160, v42, v43
	v_cvt_pk_bf16_f32 v161, v44, v45
	v_cvt_pk_bf16_f32 v162, v34, v35
	v_cvt_pk_bf16_f32 v163, v36, v37
	v_pk_mul_f32 v[26:27], v[26:27], v[144:145] op_sel_hi:[1,0]
	v_pk_mul_f32 v[28:29], v[28:29], v[144:145] op_sel_hi:[1,0]
	v_pk_mul_f32 v[18:19], v[18:19], v[144:145] op_sel_hi:[1,0]
	v_pk_mul_f32 v[20:21], v[20:21], v[144:145] op_sel_hi:[1,0]
	v_pk_mul_f32 v[30:31], v[30:31], v[144:145] op_sel_hi:[1,0]
	v_pk_mul_f32 v[32:33], v[32:33], v[144:145] op_sel_hi:[1,0]
	v_pk_mul_f32 v[22:23], v[22:23], v[144:145] op_sel_hi:[1,0]
	v_pk_mul_f32 v[24:25], v[24:25], v[144:145] op_sel_hi:[1,0]
	v_permlane16_swap_b32_e32 v160, v162
	v_permlane16_swap_b32_e32 v161, v163
	global_store_dwordx4 v[134:135], v[160:163], off nt
	v_lshl_add_u64 v[134:135], v[134:135], 0, s[12:13]
	v_pk_mul_f32 v[148:149], v[26:27], v[146:147] op_sel_hi:[1,0]
; __device__ __forceinline__ float siluf_(float x) { return x * frcp(1.0f + fexp(-x)); }
; #define SCHED __builtin_amdgcn_sched_barrier(0)
; template <int EPI>
; __device__ __forceinline__ void gemm_tile(const GemmArgs& g, int brow, int bcol, int parity, bool first, bool nvalid, int nbrow, int nbcol) {
;     ...
;   } else if constexpr (EPI == EPI_GLU) {
;     const int tn = bcol >> 8;
;     _Pragma("unroll") for (int ai = 0; ai < 2; ++ai) {
;       SCHED;
;       _Pragma("unroll") for (int m = 0; m < 4; ++m) _Pragma("unroll") for (int j = 0; j < 4; ++j) {
;         const float rs = rstd_s[lrow0 + ai * HALF + m * 16 + fq * 4 + j];
;         _Pragma("unroll") for (int n = 0; n < 2; ++n) {
;           const float gg = acc[ai][0][m][n][j] * rs, uu = acc[ai][1][m][n][j] * rs;
;           W_WRITE(m, n, j, siluf_(gg) * uu);
;         }
;       }
;       bfu* dst = g.outb + (long)(wrow0 + ai * HALF) * g.ldo + tn * 128 + (wcol0 - bcol);
;       W_STORE_BF16(dst, g.ldo);
;     }
	v_pk_mul_f32 v[150:151], v[28:29], v[146:147] op_sel_hi:[1,0]
	v_pk_mul_f32 v[152:153], v[18:19], v[146:147] op_sel_hi:[1,0]
	v_pk_mul_f32 v[154:155], v[20:21], v[146:147] op_sel_hi:[1,0]
	v_exp_f32_e32 v148, v148
	v_exp_f32_e32 v149, v149
	v_exp_f32_e32 v150, v150
	v_exp_f32_e32 v151, v151
	v_exp_f32_e32 v152, v152
	v_exp_f32_e32 v153, v153
	v_exp_f32_e32 v154, v154
	v_exp_f32_e32 v155, v155
	v_pk_add_f32 v[148:149], v[148:149], v[146:147] op_sel:[0,1] op_sel_hi:[1,1]
	v_pk_add_f32 v[150:151], v[150:151], v[146:147] op_sel:[0,1] op_sel_hi:[1,1]
	v_pk_add_f32 v[152:153], v[152:153], v[146:147] op_sel:[0,1] op_sel_hi:[1,1]
	v_pk_add_f32 v[154:155], v[154:155], v[146:147] op_sel:[0,1] op_sel_hi:[1,1]
	v_rcp_f32_e32 v148, v148
	v_rcp_f32_e32 v149, v149
	v_rcp_f32_e32 v150, v150
	v_rcp_f32_e32 v151, v151
	v_rcp_f32_e32 v152, v152
	v_rcp_f32_e32 v153, v153
	v_rcp_f32_e32 v154, v154
	v_rcp_f32_e32 v155, v155
	v_pk_mul_f32 v[26:27], v[26:27], v[148:149]
	v_pk_mul_f32 v[28:29], v[28:29], v[150:151]
	v_pk_mul_f32 v[18:19], v[18:19], v[152:153]
	v_pk_mul_f32 v[20:21], v[20:21], v[154:155]
	v_pk_mul_f32 v[26:27], v[30:31], v[26:27]
	v_pk_mul_f32 v[28:29], v[32:33], v[28:29]
	v_pk_mul_f32 v[18:19], v[22:23], v[18:19]
	v_pk_mul_f32 v[20:21], v[24:25], v[20:21]
	v_cvt_pk_bf16_f32 v156, v26, v27
	v_cvt_pk_bf16_f32 v157, v28, v29
	v_cvt_pk_bf16_f32 v158, v18, v19
	v_cvt_pk_bf16_f32 v159, v20, v21
	v_pk_mul_f32 v[6:7], v[6:7], v[144:145] op_sel:[0,1] op_sel_hi:[1,1]
	v_pk_mul_f32 v[8:9], v[8:9], v[144:145] op_sel:[0,1] op_sel_hi:[1,1]
	v_pk_mul_f32 v[2:3], v[2:3], v[144:145] op_sel:[0,1] op_sel_hi:[1,1]
	v_pk_mul_f32 v[4:5], v[4:5], v[144:145] op_sel:[0,1] op_sel_hi:[1,1]
	v_pk_mul_f32 v[14:15], v[14:15], v[144:145] op_sel:[0,1] op_sel_hi:[1,1]
	v_pk_mul_f32 v[16:17], v[16:17], v[144:145] op_sel:[0,1] op_sel_hi:[1,1]
	v_pk_mul_f32 v[10:11], v[10:11], v[144:145] op_sel:[0,1] op_sel_hi:[1,1]
	v_pk_mul_f32 v[12:13], v[12:13], v[144:145] op_sel:[0,1] op_sel_hi:[1,1]
	v_permlane16_swap_b32_e32 v156, v158
	v_permlane16_swap_b32_e32 v157, v159
	global_store_dwordx4 v[134:135], v[156:159], off nt
	v_lshl_add_u64 v[134:135], v[134:135], 0, s[12:13]
	v_pk_mul_f32 v[148:149], v[6:7], v[146:147] op_sel_hi:[1,0]
	v_pk_mul_f32 v[150:151], v[8:9], v[146:147] op_sel_hi:[1,0]
	v_pk_mul_f32 v[152:153], v[2:3], v[146:147] op_sel_hi:[1,0]
	v_pk_mul_f32 v[154:155], v[4:5], v[146:147] op_sel_hi:[1,0]
	v_exp_f32_e32 v148, v148
	v_exp_f32_e32 v149, v149
	v_exp_f32_e32 v150, v150
	v_exp_f32_e32 v151, v151
	v_exp_f32_e32 v152, v152
	v_exp_f32_e32 v153, v153
	v_exp_f32_e32 v154, v154
	v_exp_f32_e32 v155, v155
	v_pk_add_f32 v[148:149], v[148:149], v[146:147] op_sel:[0,1] op_sel_hi:[1,1]
	v_pk_add_f32 v[150:151], v[150:151], v[146:147] op_sel:[0,1] op_sel_hi:[1,1]
	v_pk_add_f32 v[152:153], v[152:153], v[146:147] op_sel:[0,1] op_sel_hi:[1,1]
	v_pk_add_f32 v[154:155], v[154:155], v[146:147] op_sel:[0,1] op_sel_hi:[1,1]
	v_rcp_f32_e32 v148, v148
	v_rcp_f32_e32 v149, v149
	v_rcp_f32_e32 v150, v150
	v_rcp_f32_e32 v151, v151
	v_rcp_f32_e32 v152, v152
	v_rcp_f32_e32 v153, v153
	v_rcp_f32_e32 v154, v154
	v_rcp_f32_e32 v155, v155
	v_pk_mul_f32 v[6:7], v[6:7], v[148:149]
	v_pk_mul_f32 v[8:9], v[8:9], v[150:151]
	v_pk_mul_f32 v[2:3], v[2:3], v[152:153]
	v_pk_mul_f32 v[4:5], v[4:5], v[154:155]
	v_pk_mul_f32 v[6:7], v[14:15], v[6:7]
	v_pk_mul_f32 v[8:9], v[16:17], v[8:9]
	v_pk_mul_f32 v[2:3], v[10:11], v[2:3]
	v_pk_mul_f32 v[4:5], v[12:13], v[4:5]
	v_cvt_pk_bf16_f32 v160, v6, v7
	v_cvt_pk_bf16_f32 v161, v8, v9
	v_cvt_pk_bf16_f32 v162, v2, v3
	v_cvt_pk_bf16_f32 v163, v4, v5
	s_nop 1
	v_permlane16_swap_b32_e32 v160, v162
	v_permlane16_swap_b32_e32 v161, v163
	global_store_dwordx4 v[134:135], v[160:163], off nt
	s_mov_b64 s[12:13], -1
	s_and_b64 vcc, exec, s[0:1]
	s_cbranch_vccnz .LBB0_173

; #define SCHED __builtin_amdgcn_sched_barrier(0)
; template <int EPI>
; __device__ __forceinline__ void gemm_tile(const GemmArgs& g, int brow, int bcol, int parity, bool first, bool nvalid, int nbrow, int nbcol) {
;     ...
;   if constexpr (EPI == EPI_PLAIN) {
;     _Pragma("unroll") for (int ai = 0; ai < 2; ++ai) _Pragma("unroll") for (int bj = 0; bj < 2; ++bj) {
;       SCHED;
;       _Pragma("unroll") for (int m = 0; m < 4; ++m) _Pragma("unroll") for (int j = 0; j < 4; ++j) {
;         const float rs = rstd_s[lrow0 + ai * HALF + m * 16 + fq * 4 + j];
;         _Pragma("unroll") for (int n = 0; n < 2; ++n) W_WRITE(m, n, j, acc[ai][bj][m][n][j] * rs);
;       }
;       bfu* dst = g.outb + (long)(wrow0 + ai * HALF) * g.ldo + g.ocol0 + wcol0 + bj * HALF;
;       W_STORE_BF16(dst, g.ldo);
;     }
.LBB0_610:
	v_mbcnt_lo_u32_b32 v130, -1, 0
	v_mbcnt_hi_u32_b32 v130, -1, v130
	s_add_i32 s21, s21, 1
	s_and_b32 s2, s33, 0x100
	s_add_i32 s2, s2, s14
	v_and_b32_e32 v131, 15, v130
	v_lshrrev_b32_e32 v132, 4, v130
	v_lshl_add_u32 v133, v131, 2, s2
	ds_read_b32 v138, v133
	ds_read_b32 v139, v133 offset:64
	ds_read_b32 v140, v133 offset:128
	ds_read_b32 v141, v133 offset:192
	ds_read_b32 v142, v133 offset:512
	ds_read_b32 v143, v133 offset:576
	ds_read_b32 v144, v133 offset:640
	ds_read_b32 v145, v133 offset:704
	v_lshlrev_b32_e32 v134, 4, v132
	v_lshlrev_b32_e32 v135, 2, v132
	v_and_b32_e32 v134, 16, v134
	v_and_b32_e32 v135, 8, v135
	s_and_b32 s3, s22, 0x7fffff8
	s_lshl_b32 s3, s3, 5
	s_lshr_b32 s12, s33, 1
	s_and_b32 s12, s12, 0x60
	s_add_i32 s3, s3, s12
	v_or_b32_e32 v134, v134, v135
	v_add_lshl_u32 v134, v134, s3, 1
	v_mov_b32_e32 v135, 0
	s_lshr_b32 s12, s33, 2
	s_and_b32 s12, s12, 64
	s_add_i32 s12, s12, s40
	v_add_u32_e32 v136, s12, v131
	s_movk_i32 s3, 0x1c00
	v_mad_u64_u32 v[134:135], vcc, v136, s3, v[134:135]
	v_lshl_add_u64 v[134:135], v[134:135], 0, s[34:35]
	s_mov_b64 s[12:13], 0x1c000
	s_mov_b64 s[14:15], 0x8c000
	s_waitcnt lgkmcnt(0)
	v_pk_mul_f32 v[122:123], v[122:123], v[138:139] op_sel_hi:[1,0]
	v_pk_mul_f32 v[124:125], v[124:125], v[138:139] op_sel_hi:[1,0]
	v_pk_mul_f32 v[126:127], v[126:127], v[138:139] op_sel_hi:[1,0]
	v_pk_mul_f32 v[128:129], v[128:129], v[138:139] op_sel_hi:[1,0]
	v_pk_mul_f32 v[90:91], v[90:91], v[138:139] op_sel_hi:[1,0]
	v_pk_mul_f32 v[92:93], v[92:93], v[138:139] op_sel_hi:[1,0]
	v_pk_mul_f32 v[94:95], v[94:95], v[138:139] op_sel_hi:[1,0]
	v_pk_mul_f32 v[96:97], v[96:97], v[138:139] op_sel_hi:[1,0]
	v_cvt_pk_bf16_f32 v146, v122, v123
	v_cvt_pk_bf16_f32 v147, v124, v125
	v_cvt_pk_bf16_f32 v148, v126, v127
	v_cvt_pk_bf16_f32 v149, v128, v129
	v_cvt_pk_bf16_f32 v150, v90, v91
	v_cvt_pk_bf16_f32 v151, v92, v93
	v_cvt_pk_bf16_f32 v152, v94, v95
	v_cvt_pk_bf16_f32 v153, v96, v97
	v_permlane16_swap_b32_e32 v146, v148
	v_permlane16_swap_b32_e32 v147, v149
	v_permlane16_swap_b32_e32 v150, v152
	v_permlane16_swap_b32_e32 v151, v153
	global_store_dwordx4 v[134:135], v[146:149], off offset:0 nt
	global_store_dwordx4 v[134:135], v[150:153], off offset:256 nt
	v_lshl_add_u64 v[134:135], v[134:135], 0, s[12:13]
	v_pk_mul_f32 v[114:115], v[114:115], v[138:139] op_sel:[0,1] op_sel_hi:[1,1]
	v_pk_mul_f32 v[116:117], v[116:117], v[138:139] op_sel:[0,1] op_sel_hi:[1,1]
	v_pk_mul_f32 v[118:119], v[118:119], v[138:139] op_sel:[0,1] op_sel_hi:[1,1]
	v_pk_mul_f32 v[120:121], v[120:121], v[138:139] op_sel:[0,1] op_sel_hi:[1,1]
	v_pk_mul_f32 v[82:83], v[82:83], v[138:139] op_sel:[0,1] op_sel_hi:[1,1]
	v_pk_mul_f32 v[84:85], v[84:85], v[138:139] op_sel:[0,1] op_sel_hi:[1,1]
	v_pk_mul_f32 v[86:87], v[86:87], v[138:139] op_sel:[0,1] op_sel_hi:[1,1]
	v_pk_mul_f32 v[88:89], v[88:89], v[138:139] op_sel:[0,1] op_sel_hi:[1,1]
	v_cvt_pk_bf16_f32 v154, v114, v115
	v_cvt_pk_bf16_f32 v155, v116, v117
	v_cvt_pk_bf16_f32 v156, v118, v119
	v_cvt_pk_bf16_f32 v157, v120, v121
	v_cvt_pk_bf16_f32 v158, v82, v83
	v_cvt_pk_bf16_f32 v159, v84, v85
	v_cvt_pk_bf16_f32 v160, v86, v87
	v_cvt_pk_bf16_f32 v161, v88, v89
	v_permlane16_swap_b32_e32 v154, v156
	v_permlane16_swap_b32_e32 v155, v157
	v_permlane16_swap_b32_e32 v158, v160
	v_permlane16_swap_b32_e32 v159, v161
	global_store_dwordx4 v[134:135], v[154:157], off offset:0 nt
	global_store_dwordx4 v[134:135], v[158:161], off offset:256 nt
	v_lshl_add_u64 v[134:135], v[134:135], 0, s[12:13]
	v_pk_mul_f32 v[106:107], v[106:107], v[140:141] op_sel_hi:[1,0]
	v_pk_mul_f32 v[108:109], v[108:109], v[140:141] op_sel_hi:[1,0]
	v_pk_mul_f32 v[110:111], v[110:111], v[140:141] op_sel_hi:[1,0]
	v_pk_mul_f32 v[112:113], v[112:113], v[140:141] op_sel_hi:[1,0]
	v_pk_mul_f32 v[74:75], v[74:75], v[140:141] op_sel_hi:[1,0]
	v_pk_mul_f32 v[76:77], v[76:77], v[140:141] op_sel_hi:[1,0]
	v_pk_mul_f32 v[78:79], v[78:79], v[140:141] op_sel_hi:[1,0]
	v_pk_mul_f32 v[80:81], v[80:81], v[140:141] op_sel_hi:[1,0]
	v_cvt_pk_bf16_f32 v146, v106, v107
	v_cvt_pk_bf16_f32 v147, v108, v109
	v_cvt_pk_bf16_f32 v148, v110, v111
	v_cvt_pk_bf16_f32 v149, v112, v113
	v_cvt_pk_bf16_f32 v150, v74, v75
	v_cvt_pk_bf16_f32 v151, v76, v77
	v_cvt_pk_bf16_f32 v152, v78, v79
	v_cvt_pk_bf16_f32 v153, v80, v81
	v_permlane16_swap_b32_e32 v146, v148
	v_permlane16_swap_b32_e32 v147, v149
	v_permlane16_swap_b32_e32 v150, v152
	v_permlane16_swap_b32_e32 v151, v153
	global_store_dwordx4 v[134:135], v[146:149], off offset:0 nt
	global_store_dwordx4 v[134:135], v[150:153], off offset:256 nt
	v_lshl_add_u64 v[134:135], v[134:135], 0, s[12:13]
	v_pk_mul_f32 v[98:99], v[98:99], v[140:141] op_sel:[0,1] op_sel_hi:[1,1]
	v_pk_mul_f32 v[100:101], v[100:101], v[140:141] op_sel:[0,1] op_sel_hi:[1,1]
	v_pk_mul_f32 v[102:103], v[102:103], v[140:141] op_sel:[0,1] op_sel_hi:[1,1]
	v_pk_mul_f32 v[104:105], v[104:105], v[140:141] op_sel:[0,1] op_sel_hi:[1,1]
	v_pk_mul_f32 v[66:67], v[66:67], v[140:141] op_sel:[0,1] op_sel_hi:[1,1]
	v_pk_mul_f32 v[68:69], v[68:69], v[140:141] op_sel:[0,1] op_sel_hi:[1,1]
	v_pk_mul_f32 v[70:71], v[70:71], v[140:141] op_sel:[0,1] op_sel_hi:[1,1]
; #define SCHED __builtin_amdgcn_sched_barrier(0)
; template <int EPI>
; __device__ __forceinline__ void gemm_tile(const GemmArgs& g, int brow, int bcol, int parity, bool first, bool nvalid, int nbrow, int nbcol) {
;     ...
;   if constexpr (EPI == EPI_PLAIN) {
;     _Pragma("unroll") for (int ai = 0; ai < 2; ++ai) _Pragma("unroll") for (int bj = 0; bj < 2; ++bj) {
;       SCHED;
;       _Pragma("unroll") for (int m = 0; m < 4; ++m) _Pragma("unroll") for (int j = 0; j < 4; ++j) {
;         const float rs = rstd_s[lrow0 + ai * HALF + m * 16 + fq * 4 + j];
;         _Pragma("unroll") for (int n = 0; n < 2; ++n) W_WRITE(m, n, j, acc[ai][bj][m][n][j] * rs);
;       }
;       bfu* dst = g.outb + (long)(wrow0 + ai * HALF) * g.ldo + g.ocol0 + wcol0 + bj * HALF;
;       W_STORE_BF16(dst, g.ldo);
;     }
	v_pk_mul_f32 v[72:73], v[72:73], v[140:141] op_sel:[0,1] op_sel_hi:[1,1]
	v_cvt_pk_bf16_f32 v154, v98, v99
	v_cvt_pk_bf16_f32 v155, v100, v101
	v_cvt_pk_bf16_f32 v156, v102, v103
	v_cvt_pk_bf16_f32 v157, v104, v105
	v_cvt_pk_bf16_f32 v158, v66, v67
	v_cvt_pk_bf16_f32 v159, v68, v69
	v_cvt_pk_bf16_f32 v160, v70, v71
	v_cvt_pk_bf16_f32 v161, v72, v73
	v_permlane16_swap_b32_e32 v154, v156
	v_permlane16_swap_b32_e32 v155, v157
	v_permlane16_swap_b32_e32 v158, v160
	v_permlane16_swap_b32_e32 v159, v161
	global_store_dwordx4 v[134:135], v[154:157], off offset:0 nt
	global_store_dwordx4 v[134:135], v[158:161], off offset:256 nt
	v_lshl_add_u64 v[134:135], v[134:135], 0, s[14:15]
	v_pk_mul_f32 v[58:59], v[58:59], v[142:143] op_sel_hi:[1,0]
	v_pk_mul_f32 v[60:61], v[60:61], v[142:143] op_sel_hi:[1,0]
	v_pk_mul_f32 v[62:63], v[62:63], v[142:143] op_sel_hi:[1,0]
	v_pk_mul_f32 v[64:65], v[64:65], v[142:143] op_sel_hi:[1,0]
	v_pk_mul_f32 v[26:27], v[26:27], v[142:143] op_sel_hi:[1,0]
	v_pk_mul_f32 v[28:29], v[28:29], v[142:143] op_sel_hi:[1,0]
	v_pk_mul_f32 v[30:31], v[30:31], v[142:143] op_sel_hi:[1,0]
	v_pk_mul_f32 v[32:33], v[32:33], v[142:143] op_sel_hi:[1,0]
	v_cvt_pk_bf16_f32 v146, v58, v59
	v_cvt_pk_bf16_f32 v147, v60, v61
	v_cvt_pk_bf16_f32 v148, v62, v63
	v_cvt_pk_bf16_f32 v149, v64, v65
	v_cvt_pk_bf16_f32 v150, v26, v27
	v_cvt_pk_bf16_f32 v151, v28, v29
	v_cvt_pk_bf16_f32 v152, v30, v31
	v_cvt_pk_bf16_f32 v153, v32, v33
	v_permlane16_swap_b32_e32 v146, v148
	v_permlane16_swap_b32_e32 v147, v149
	v_permlane16_swap_b32_e32 v150, v152
	v_permlane16_swap_b32_e32 v151, v153
	global_store_dwordx4 v[134:135], v[146:149], off offset:0 nt
	global_store_dwordx4 v[134:135], v[150:153], off offset:256 nt
	v_lshl_add_u64 v[134:135], v[134:135], 0, s[12:13]
	v_pk_mul_f32 v[50:51], v[50:51], v[142:143] op_sel:[0,1] op_sel_hi:[1,1]
	v_pk_mul_f32 v[52:53], v[52:53], v[142:143] op_sel:[0,1] op_sel_hi:[1,1]
	v_pk_mul_f32 v[54:55], v[54:55], v[142:143] op_sel:[0,1] op_sel_hi:[1,1]
	v_pk_mul_f32 v[56:57], v[56:57], v[142:143] op_sel:[0,1] op_sel_hi:[1,1]
	v_pk_mul_f32 v[18:19], v[18:19], v[142:143] op_sel:[0,1] op_sel_hi:[1,1]
	v_pk_mul_f32 v[20:21], v[20:21], v[142:143] op_sel:[0,1] op_sel_hi:[1,1]
	v_pk_mul_f32 v[22:23], v[22:23], v[142:143] op_sel:[0,1] op_sel_hi:[1,1]
	v_pk_mul_f32 v[24:25], v[24:25], v[142:143] op_sel:[0,1] op_sel_hi:[1,1]
	v_cvt_pk_bf16_f32 v154, v50, v51
	v_cvt_pk_bf16_f32 v155, v52, v53
	v_cvt_pk_bf16_f32 v156, v54, v55
	v_cvt_pk_bf16_f32 v157, v56, v57
	v_cvt_pk_bf16_f32 v158, v18, v19
	v_cvt_pk_bf16_f32 v159, v20, v21
	v_cvt_pk_bf16_f32 v160, v22, v23
	v_cvt_pk_bf16_f32 v161, v24, v25
	v_permlane16_swap_b32_e32 v154, v156
	v_permlane16_swap_b32_e32 v155, v157
	v_permlane16_swap_b32_e32 v158, v160
	v_permlane16_swap_b32_e32 v159, v161
	global_store_dwordx4 v[134:135], v[154:157], off offset:0 nt
	global_store_dwordx4 v[134:135], v[158:161], off offset:256 nt
	v_lshl_add_u64 v[134:135], v[134:135], 0, s[12:13]
	v_pk_mul_f32 v[42:43], v[42:43], v[144:145] op_sel_hi:[1,0]
	v_pk_mul_f32 v[44:45], v[44:45], v[144:145] op_sel_hi:[1,0]
	v_pk_mul_f32 v[46:47], v[46:47], v[144:145] op_sel_hi:[1,0]
	v_pk_mul_f32 v[48:49], v[48:49], v[144:145] op_sel_hi:[1,0]
	v_pk_mul_f32 v[10:11], v[10:11], v[144:145] op_sel_hi:[1,0]
	v_pk_mul_f32 v[12:13], v[12:13], v[144:145] op_sel_hi:[1,0]
	v_pk_mul_f32 v[14:15], v[14:15], v[144:145] op_sel_hi:[1,0]
	v_pk_mul_f32 v[16:17], v[16:17], v[144:145] op_sel_hi:[1,0]
	v_cvt_pk_bf16_f32 v146, v42, v43
	v_cvt_pk_bf16_f32 v147, v44, v45
	v_cvt_pk_bf16_f32 v148, v46, v47
	v_cvt_pk_bf16_f32 v149, v48, v49
	v_cvt_pk_bf16_f32 v150, v10, v11
	v_cvt_pk_bf16_f32 v151, v12, v13
	v_cvt_pk_bf16_f32 v152, v14, v15
	v_cvt_pk_bf16_f32 v153, v16, v17
	v_permlane16_swap_b32_e32 v146, v148
	v_permlane16_swap_b32_e32 v147, v149
	v_permlane16_swap_b32_e32 v150, v152
	v_permlane16_swap_b32_e32 v151, v153
	global_store_dwordx4 v[134:135], v[146:149], off offset:0 nt
	global_store_dwordx4 v[134:135], v[150:153], off offset:256 nt
	v_lshl_add_u64 v[134:135], v[134:135], 0, s[12:13]
	v_pk_mul_f32 v[34:35], v[34:35], v[144:145] op_sel:[0,1] op_sel_hi:[1,1]
	v_pk_mul_f32 v[36:37], v[36:37], v[144:145] op_sel:[0,1] op_sel_hi:[1,1]
	v_pk_mul_f32 v[38:39], v[38:39], v[144:145] op_sel:[0,1] op_sel_hi:[1,1]
	v_pk_mul_f32 v[40:41], v[40:41], v[144:145] op_sel:[0,1] op_sel_hi:[1,1]
	v_pk_mul_f32 v[2:3], v[2:3], v[144:145] op_sel:[0,1] op_sel_hi:[1,1]
	v_pk_mul_f32 v[4:5], v[4:5], v[144:145] op_sel:[0,1] op_sel_hi:[1,1]
	v_pk_mul_f32 v[6:7], v[6:7], v[144:145] op_sel:[0,1] op_sel_hi:[1,1]
	v_pk_mul_f32 v[8:9], v[8:9], v[144:145] op_sel:[0,1] op_sel_hi:[1,1]
	v_cvt_pk_bf16_f32 v154, v34, v35
	v_cvt_pk_bf16_f32 v155, v36, v37
	v_cvt_pk_bf16_f32 v156, v38, v39
	v_cvt_pk_bf16_f32 v157, v40, v41
	v_cvt_pk_bf16_f32 v158, v2, v3
	v_cvt_pk_bf16_f32 v159, v4, v5
	v_cvt_pk_bf16_f32 v160, v6, v7
	v_cvt_pk_bf16_f32 v161, v8, v9
	v_permlane16_swap_b32_e32 v154, v156
	v_permlane16_swap_b32_e32 v155, v157
	v_permlane16_swap_b32_e32 v158, v160
	v_permlane16_swap_b32_e32 v159, v161
	global_store_dwordx4 v[134:135], v[154:157], off offset:0 nt
	global_store_dwordx4 v[134:135], v[158:161], off offset:256 nt
